# combined candidate with the post-QK wait states trimmed to the required distance (V fragment reads act as fillers)
# speedup vs baseline: 1.0136x; 1.0004x over previous
.Lat_skipld:
	s_waitcnt lgkmcnt(3)
	v_mfma_f32_32x32x16_bf16 v[64:79], v[236:239], v[136:139], v[64:79]
	v_mfma_f32_32x32x16_bf16 v[96:111], v[236:239], v[160:163], v[96:111]
	ds_read_b128 v[236:239], v235 offset:128
	s_waitcnt lgkmcnt(3)
	v_mfma_f32_32x32x16_bf16 v[80:95], v[240:243], v[136:139], v[80:95]
	v_mfma_f32_32x32x16_bf16 v[112:127], v[240:243], v[160:163], v[112:127]
	ds_read_b128 v[240:243], v235 offset:6784
	s_waitcnt lgkmcnt(3)
	v_mfma_f32_32x32x16_bf16 v[64:79], v[244:247], v[140:143], v[64:79]
	v_mfma_f32_32x32x16_bf16 v[96:111], v[244:247], v[164:167], v[96:111]
	ds_read_b128 v[244:247], v235 offset:160
	s_waitcnt lgkmcnt(3)
	v_mfma_f32_32x32x16_bf16 v[80:95], v[248:251], v[140:143], v[80:95]
	v_mfma_f32_32x32x16_bf16 v[112:127], v[248:251], v[164:167], v[112:127]
	ds_read_b128 v[248:251], v235 offset:6816
	s_waitcnt lgkmcnt(3)
	v_mfma_f32_32x32x16_bf16 v[64:79], v[236:239], v[144:147], v[64:79]
	v_mfma_f32_32x32x16_bf16 v[96:111], v[236:239], v[168:171], v[96:111]
	s_waitcnt lgkmcnt(2)
	v_mfma_f32_32x32x16_bf16 v[80:95], v[240:243], v[144:147], v[80:95]
	v_mfma_f32_32x32x16_bf16 v[112:127], v[240:243], v[168:171], v[112:127]
	s_waitcnt lgkmcnt(1)
	v_mfma_f32_32x32x16_bf16 v[64:79], v[244:247], v[148:151], v[64:79]
	v_mfma_f32_32x32x16_bf16 v[96:111], v[244:247], v[172:175], v[96:111]
	s_waitcnt lgkmcnt(0)
	v_mfma_f32_32x32x16_bf16 v[80:95], v[248:251], v[148:151], v[80:95]
	v_mfma_f32_32x32x16_bf16 v[112:127], v[248:251], v[172:175], v[112:127]
	ds_read_b128 v[236:239], v218 offset:13312
	ds_read_b128 v[240:243], v218 offset:17920
	ds_read_b128 v[244:247], v218 offset:13344
	ds_read_b128 v[248:251], v218 offset:17952
	s_nop 6
	v_max3_f32 v214, v64, v65, v66
	v_max3_f32 v215, v80, v81, v82
	v_max3_f32 v216, v96, v97, v98
	v_max3_f32 v217, v112, v113, v114
	v_max3_f32 v214, v214, v67, v68
	v_max3_f32 v215, v215, v83, v84
	v_max3_f32 v216, v216, v99, v100
	v_max3_f32 v217, v217, v115, v116
	v_max3_f32 v214, v214, v69, v70
	v_max3_f32 v215, v215, v85, v86
	v_max3_f32 v216, v216, v101, v102
	v_max3_f32 v217, v217, v117, v118
	v_max3_f32 v214, v214, v71, v72
	v_max3_f32 v215, v215, v87, v88
	v_max3_f32 v216, v216, v103, v104
	v_max3_f32 v217, v217, v119, v120
	v_max3_f32 v214, v214, v73, v74
	v_max3_f32 v215, v215, v89, v90
	v_max3_f32 v216, v216, v105, v106
	v_max3_f32 v217, v217, v121, v122
	v_max3_f32 v214, v214, v75, v76
	v_max3_f32 v215, v215, v91, v92
	v_max3_f32 v216, v216, v107, v108
	v_max3_f32 v217, v217, v123, v124
	v_max3_f32 v214, v214, v77, v78
	v_max3_f32 v215, v215, v93, v94
	v_max3_f32 v216, v216, v109, v110
	v_max3_f32 v217, v217, v125, v126
	v_max_f32_e32 v214, v214, v79
	v_max_f32_e32 v215, v215, v95
	v_max_f32_e32 v216, v216, v111
	v_max_f32_e32 v217, v217, v127
	v_max_f32_e32 v214, v214, v215
	v_max_f32_e32 v216, v216, v217
	v_mov_b32_e32 v215, v214
	v_mov_b32_e32 v217, v216
	s_nop 1
	v_permlane32_swap_b32 v214, v215
	v_permlane32_swap_b32 v216, v217
	v_max_f32_e32 v214, v214, v215
	v_max_f32_e32 v216, v216, v217
	v_cmp_lt_f32_e32 vcc, s56, v214
	s_cbranch_vccz .Lat_nr0
	v_max_f32_e32 v215, 0, v214
	v_sub_f32_e32 v196, 0, v215
	v_exp_f32_e32 v196, v196
	v_add_f32_e32 v233, v233, v215
	s_nop 0
	v_mul_f32_e32 v202, v196, v202
	v_mul_f32_e32 v0, v196, v0
	v_mul_f32_e32 v1, v196, v1
	v_mul_f32_e32 v2, v196, v2
	v_mul_f32_e32 v3, v196, v3
	v_mul_f32_e32 v4, v196, v4
	v_mul_f32_e32 v5, v196, v5
	v_mul_f32_e32 v6, v196, v6
	v_mul_f32_e32 v7, v196, v7
	v_mul_f32_e32 v8, v196, v8
	v_mul_f32_e32 v9, v196, v9
	v_mul_f32_e32 v10, v196, v10
	v_mul_f32_e32 v11, v196, v11
	v_mul_f32_e32 v12, v196, v12
	v_mul_f32_e32 v13, v196, v13
	v_mul_f32_e32 v14, v196, v14
	v_mul_f32_e32 v15, v196, v15
	v_mul_f32_e32 v16, v196, v16
	v_mul_f32_e32 v17, v196, v17
	v_mul_f32_e32 v18, v196, v18
	v_mul_f32_e32 v19, v196, v19
	v_mul_f32_e32 v20, v196, v20
	v_mul_f32_e32 v21, v196, v21
	v_mul_f32_e32 v22, v196, v22
	v_mul_f32_e32 v23, v196, v23
	v_mul_f32_e32 v24, v196, v24
	v_mul_f32_e32 v25, v196, v25
	v_mul_f32_e32 v26, v196, v26
	v_mul_f32_e32 v27, v196, v27
	v_mul_f32_e32 v28, v196, v28
	v_mul_f32_e32 v29, v196, v29
	v_mul_f32_e32 v30, v196, v30
	v_mul_f32_e32 v31, v196, v31
	v_sub_f32_e32 v64, v64, v215
	v_sub_f32_e32 v65, v65, v215
	v_sub_f32_e32 v66, v66, v215
	v_sub_f32_e32 v67, v67, v215
	v_sub_f32_e32 v68, v68, v215
	v_sub_f32_e32 v69, v69, v215
	v_sub_f32_e32 v70, v70, v215
	v_sub_f32_e32 v71, v71, v215
	v_sub_f32_e32 v72, v72, v215
	v_sub_f32_e32 v73, v73, v215
	v_sub_f32_e32 v74, v74, v215
	v_sub_f32_e32 v75, v75, v215
	v_sub_f32_e32 v76, v76, v215
	v_sub_f32_e32 v77, v77, v215
	v_sub_f32_e32 v78, v78, v215
	v_sub_f32_e32 v79, v79, v215
	v_sub_f32_e32 v80, v80, v215
	v_sub_f32_e32 v81, v81, v215
	v_sub_f32_e32 v82, v82, v215
	v_sub_f32_e32 v83, v83, v215
	v_sub_f32_e32 v84, v84, v215
	v_sub_f32_e32 v85, v85, v215
	v_sub_f32_e32 v86, v86, v215
	v_sub_f32_e32 v87, v87, v215
	v_sub_f32_e32 v88, v88, v215
	v_sub_f32_e32 v89, v89, v215
	v_sub_f32_e32 v90, v90, v215
	v_sub_f32_e32 v91, v91, v215
	v_sub_f32_e32 v92, v92, v215
	v_sub_f32_e32 v93, v93, v215
	v_sub_f32_e32 v94, v94, v215
	v_sub_f32_e32 v95, v95, v215
